# SB key loop: the eight stop-flag reads issued as two 16-byte LDS reads with one wait (was eight dependent round trips per step)
# speedup vs baseline: 1.0043x; 1.0043x over previous
.LBB0_364:
	s_and_b32 s90, s86, 8
	s_xor_b32 s82, s90, 8
	s_lshl_b32 s82, s82, 2
	s_add_i32 s82, s82, 0
	s_add_i32 s82, s82, 0x241c0
	v_mov_b32_e32 v82, s82
	ds_read_b128 v[136:139], v82
	ds_read_b128 v[140:143], v82 offset:16
	s_waitcnt lgkmcnt(0)
	v_and_b32_e32 v136, v136, v137
	v_and_b32_e32 v138, v138, v139
	v_and_b32_e32 v140, v140, v141
	v_and_b32_e32 v142, v142, v143
	v_and_b32_e32 v136, v136, v138
	v_and_b32_e32 v140, v140, v142
	v_and_b32_e32 v82, v136, v140
	s_nop 0
	v_readfirstlane_b32 s82, v82
	s_cmp_lg_u32 s82, 0
	s_cselect_b64 s[82:83], -1, 0
	s_and_b64 vcc, exec, s[82:83]
	s_cbranch_vccnz .LBB0_355
	s_cmp_lt_i32 s84, 3
	s_cbranch_scc0 .LBB0_373
	s_andn2_b64 vcc, exec, s[72:73]
	s_cbranch_vccz .LBB0_374
